# as v98 with 232 GEMM1 workgroups (multiple of 8, keeps the XCD-aware unit order) and 24 converting workgroups
# baseline (speedup 1.0000x reference)
.LBB0_248:
.LBB0_249:
	s_cmp_lt_i32 s86, 2
	s_cselect_b64 s[2:3], -1, 0
	s_add_u32 s62, s84, 0xb000000
	s_addc_u32 s63, s85, 0
	s_add_u32 s64, s84, 0xf800000
	s_addc_u32 s65, s85, 0
	s_add_u32 s70, s84, 0x13800000
	s_addc_u32 s71, s85, 0
	s_add_u32 s4, s84, 0x17800000
	s_addc_u32 s5, s85, 0
	s_and_b64 s[0:1], s[2:3], s[0:1]
	v_writelane_b32 v228, s4, 14
	s_andn2_b64 vcc, exec, s[0:1]
	s_nop 0
	v_writelane_b32 v228, s5, 15
	s_cbranch_vccnz .LBB0_392
	s_cmp_lg_u32 s88, 0x100
	s_cbranch_scc1 .Lp1_all
	s_cmp_lt_u32 s94, 0xe8
	s_cbranch_scc1 .Lp1_gemm
	v_readlane_b32 s0, v228, 12
	v_readlane_b32 s1, v228, 13
	s_sub_u32 s0, s0, 0xb0
	s_subb_u32 s1, s1, 0
	s_load_dwordx16 s[60:75], s[0:1], 0x0
	s_load_dwordx4 s[76:79], s[0:1], 0x80
	s_add_i32 s94, s94, 24
	s_movk_i32 s88, 96
	s_mov_b32 s101, 2
	s_movk_i32 s99, 0x39ff
	s_movk_i32 s100, 0x1b00
	s_waitcnt lgkmcnt(0)
	s_branch .Lp0_entry
.Lp1_conv_ret:
	s_sub_i32 s94, s94, 24
	v_readlane_b32 s88, v228, 6
	s_mov_b32 s101, 0
	s_add_u32 s62, s84, 0xb000000
	s_addc_u32 s63, s85, 0
	s_add_u32 s64, s84, 0xf800000
	s_addc_u32 s65, s85, 0
	s_add_u32 s70, s84, 0x13800000
	s_addc_u32 s71, s85, 0
	s_add_u32 s4, s84, 0x17800000
	s_addc_u32 s5, s85, 0
	s_nop 0
	v_writelane_b32 v228, s94, 16
	v_writelane_b32 v228, s4, 14
	v_writelane_b32 v228, s5, 15
	s_waitcnt vmcnt(0) lgkmcnt(0)
	s_barrier
	s_mov_b64 s[0:1], -1
	s_branch .LBB0_392
.Lp1_gemm:
	s_movk_i32 s88, 0xe8

.LBB0_266:
	s_add_i32 s41, s41, 1
	s_cmp_ge_i32 s41, s35
	s_cbranch_scc0 .LBB0_268
	s_cmp_lg_u32 s88, 0xe8
	s_cbranch_scc1 .Lp1_nodef
	s_cmp_lg_u32 s41, s35
	s_cbranch_scc1 .Lp1_nodef
	s_sub_i32 s12, s94, 0x90
	s_cmp_lt_u32 s12, 0x50
	s_cbranch_scc0 .Lp1_nodef
	s_cmp_lt_u32 s12, 0x40
	s_cbranch_scc0 .Lp1_defkv
	s_and_b32 s14, s12, 1
	s_add_i32 s14, s14, 48
	s_lshr_b32 s12, s12, 1
	s_branch .LBB0_275
